# DeltaNet chunk scan: all 12 next-chunk prefetch loads interleaved one-by-one with the LDS fragment reads after the barrier (none left in the staging segment)
# baseline (speedup 1.0000x reference)
.LBB0_286:
	v_add_u32_e32 v101, v43, v107
	s_add_u32 s18, s94, s10
	s_waitcnt lgkmcnt(0)
	s_barrier
	s_waitcnt vmcnt(4)
	v_perm_b32 v99, v147, v103, s78
	v_perm_b32 v97, v146, v105, s78
	ds_write_b128 v76, v[2:5]
	ds_write_b128 v101, v[6:9] offset:34816
	ds_write_b128 v76, v[10:13] offset:53248
	ds_write_b128 v78, v[14:17]
	ds_write_b128 v145, v[18:21] offset:34816
	ds_write_b128 v78, v[22:25] offset:53248
	ds_write_b128 v129, v[26:29]
	v_lshl_add_u64 v[2:3], s[94:95], 0, v[108:109]
	v_lshl_add_u64 v[6:7], s[94:95], 0, v[110:111]
	v_lshl_add_u64 v[10:11], s[94:95], 0, v[126:127]
	v_lshl_add_u64 v[14:15], s[94:95], 0, v[114:115]
	v_lshl_add_u64 v[18:19], s[94:95], 0, v[116:117]
	v_lshl_add_u64 v[22:23], s[94:95], 0, v[124:125]
	v_lshl_add_u64 v[26:27], s[94:95], 0, v[120:121]
	v_lshl_add_u64 v[146:147], s[94:95], 0, v[122:123]
	v_lshl_add_u64 v[148:149], s[94:95], 0, v[118:119]
	s_addc_u32 s19, s95, s12
	v_mov_b32_e32 v128, v106
	v_pk_mul_f32 v[32:33], v[32:33], v[128:129] op_sel_hi:[1,0]
	v_pk_mul_f32 v[30:31], v[30:31], v[128:129] op_sel_hi:[1,0]
	v_pk_mul_f32 v[36:37], v[36:37], v[128:129] op_sel_hi:[1,0]
	v_pk_mul_f32 v[34:35], v[34:35], v[128:129] op_sel_hi:[1,0]
	s_add_u32 s10, s10, 4
	s_addc_u32 s12, s12, 0
	s_add_i32 s8, s8, -1
	s_nop 0
	s_waitcnt lgkmcnt(0)
	s_barrier
	ds_read_b128 v[180:183], v130
	global_load_dwordx4 v[2:5], v[2:3], off
	ds_read_b128 v[196:199], v131 offset:53248
	global_load_dwordx4 v[6:9], v[6:7], off
	ds_read_b128 v[184:187], v130 offset:64
	global_load_dwordx4 v[10:13], v[10:11], off
	ds_read_b128 v[200:203], v131 offset:53312
	global_load_dwordx4 v[14:17], v[14:15], off
	ds_read_b128 v[188:191], v130 offset:128
	global_load_dwordx4 v[18:21], v[18:19], off
	ds_read_b128 v[208:211], v131 offset:53376
	global_load_dwordx4 v[22:25], v[22:23], off
	ds_read_b128 v[192:195], v130 offset:192
	global_load_dwordx4 v[26:29], v[26:27], off
	ds_read_b128 v[212:215], v131 offset:53440
	global_load_ushort v103, v[146:147], off
	ds_read_b128 v[216:219], v131
	global_load_ushort v147, v[148:149], off offset:-256
	ds_read_b128 v[220:223], v131 offset:64
	global_load_ushort v105, v[148:149], off
	ds_read_b128 v[224:227], v131 offset:128
	global_load_ushort v146, v[148:149], off offset:256
	ds_read_b128 v[228:231], v131 offset:192
	global_load_dword v106, v1, s[18:19]
	v_lshl_add_u64 v[108:109], v[108:109], 0, s[56:57]
	v_lshl_add_u64 v[110:111], v[110:111], 0, s[56:57]
	v_lshl_add_u64 v[114:115], v[114:115], 0, s[56:57]
	s_waitcnt lgkmcnt(10)
	v_mfma_f32_16x16x32_bf16 v[152:155], v[196:199], v[180:183], 0
	ds_read_b128 v[232:235], v133
	v_lshl_add_u64 v[116:117], v[116:117], 0, s[56:57]
	s_waitcnt lgkmcnt(9)
	v_mfma_f32_16x16x32_bf16 v[152:155], v[200:203], v[184:187], v[152:155]
	ds_read_b128 v[236:239], v133 offset:64
	v_lshl_add_u64 v[118:119], v[118:119], 0, s[4:5]
	s_waitcnt lgkmcnt(8)
	v_mfma_f32_16x16x32_bf16 v[152:155], v[208:211], v[188:191], v[152:155]
	ds_read_b128 v[240:243], v135 offset:34816
	v_lshl_add_u64 v[120:121], v[120:121], 0, s[56:57]
	s_waitcnt lgkmcnt(7)
	v_mfma_f32_16x16x32_bf16 v[152:155], v[212:215], v[192:195], v[152:155]
	ds_read_b128 v[176:179], v135 offset:34880
	v_lshl_add_u64 v[122:123], v[122:123], 0, s[4:5]
	s_waitcnt lgkmcnt(7)
	v_mfma_f32_16x16x32_bf16 v[148:151], v[216:219], v[180:183], 0
	v_lshl_add_u64 v[124:125], v[124:125], 0, s[4:5]
	s_waitcnt lgkmcnt(6)
	v_mfma_f32_16x16x32_bf16 v[148:151], v[220:223], v[184:187], v[148:151]
	v_lshl_add_u64 v[126:127], v[126:127], 0, s[4:5]
	s_waitcnt lgkmcnt(5)
	v_mfma_f32_16x16x32_bf16 v[148:151], v[224:227], v[188:191], v[148:151]
	v_and_b32_e32 v157, 0xffff0000, v99
	s_waitcnt lgkmcnt(4)
	v_mfma_f32_16x16x32_bf16 v[148:151], v[228:231], v[192:195], v[148:151]
	v_lshlrev_b32_e32 v156, 16, v99
	v_and_b32_e32 v159, 0xffff0000, v97
	v_lshlrev_b32_e32 v158, 16, v97
	v_pk_add_f32 v[152:153], v[156:157], v[152:153] neg_lo:[0,1] neg_hi:[0,1]
	v_pk_add_f32 v[154:155], v[158:159], v[154:155] neg_lo:[0,1] neg_hi:[0,1]
	v_cvt_pk_bf16_f32 v152, v152, v153
	v_cvt_pk_bf16_f32 v153, v154, v155
	ds_write_b64 v132, v[152:153]
	s_waitcnt lgkmcnt(0)
	s_barrier
	ds_read_b128 v[180:183], v134
	ds_read_b128 v[184:187], v134 offset:64
	ds_read_b128 v[188:191], v136
	ds_read_b128 v[192:195], v136 offset:64
	ds_read_b128 v[196:199], v136 offset:2304
	ds_read_b128 v[200:203], v136 offset:2368
	s_waitcnt lgkmcnt(5)
	v_mfma_f32_16x16x32_bf16 v[148:151], v[232:235], v[180:183], v[148:151]
	v_lshl_add_u64 v[152:153], s[94:95], 0, v[112:113]
	s_waitcnt lgkmcnt(4)
	v_mfma_f32_16x16x32_bf16 v[148:151], v[236:239], v[184:187], v[148:151]
	v_lshl_add_u64 v[112:113], v[112:113], 0, s[4:5]
	s_waitcnt lgkmcnt(3)
	v_mfma_f32_16x16x32_bf16 v[30:33], v[240:243], v[188:191], v[30:33]
	s_waitcnt lgkmcnt(2)
	v_mfma_f32_16x16x32_bf16 v[30:33], v[176:179], v[192:195], v[30:33]
	s_waitcnt lgkmcnt(1)
	v_mfma_f32_16x16x32_bf16 v[34:37], v[240:243], v[196:199], v[34:37]
	s_waitcnt lgkmcnt(0)
	v_mfma_f32_16x16x32_bf16 v[34:37], v[176:179], v[200:203], v[34:37]
	s_nop 0
	v_cvt_pk_bf16_f32 v97, v148, s0
	global_store_short v[152:153], v97, off offset:-512
	v_cvt_pk_bf16_f32 v97, v149, s0
	global_store_short v[152:153], v97, off offset:-256
	v_cvt_pk_bf16_f32 v97, v150, s0
	global_store_short v[152:153], v97, off
	v_cvt_pk_bf16_f32 v97, v151, s0
	global_store_short v[152:153], v97, off offset:256
	v_cvt_pk_bf16_f32 v156, v30, v31
	v_cvt_pk_bf16_f32 v157, v32, v33
	ds_write_b64 v137, v[156:157]
	v_cvt_pk_bf16_f32 v158, v34, v35
	v_cvt_pk_bf16_f32 v159, v36, v37
	ds_write_b64 v137, v[158:159] offset:4352
	s_cmp_eq_u32 s8, 0
	s_cbranch_scc0 .LBB0_286
	s_waitcnt lgkmcnt(0)
	s_barrier
	s_waitcnt vmcnt(4)
	ds_write_b128 v76, v[2:5]
	ds_write_b128 v101, v[6:9] offset:34816
	ds_write_b128 v76, v[10:13] offset:53248
	ds_write_b128 v78, v[14:17]
	ds_write_b128 v145, v[18:21] offset:34816
	ds_write_b128 v78, v[22:25] offset:53248
	ds_write_b128 v129, v[26:29]
	s_waitcnt lgkmcnt(0)
	s_barrier
	ds_read_b128 v[2:5], v131 offset:53248
	ds_read_b128 v[6:9], v130
	ds_read_b128 v[10:13], v130 offset:64
	ds_read_b128 v[14:17], v131 offset:53312
	s_waitcnt lgkmcnt(2)
	v_mfma_f32_16x16x32_bf16 v[2:5], v[2:5], v[6:9], 0
	ds_read_b128 v[18:21], v131
	ds_read_b128 v[22:25], v131 offset:64
	v_lshlrev_b32_e32 v27, 16, v147
	v_lshlrev_b32_e32 v26, 16, v103
	s_waitcnt lgkmcnt(2)
	v_mfma_f32_16x16x32_bf16 v[2:5], v[14:17], v[10:13], v[2:5]
	ds_read_b128 v[14:17], v131 offset:53376
	s_lshl_b32 s8, s11, 1
	s_add_u32 s6, s6, s8
	s_waitcnt lgkmcnt(2)
	v_mfma_f32_16x16x32_bf16 v[6:9], v[18:21], v[6:9], 0
	s_addc_u32 s7, s7, 0
	s_add_i32 s2, s2, s50
	s_cmpk_gt_i32 s2, 0xff
	s_waitcnt lgkmcnt(1)
	v_mfma_f32_16x16x32_bf16 v[6:9], v[22:25], v[10:13], v[6:9]
	ds_read_b128 v[10:13], v131 offset:53440
	ds_read_b128 v[18:21], v130 offset:128
	ds_read_b128 v[22:25], v130 offset:192
	s_waitcnt lgkmcnt(1)
	v_mfma_f32_16x16x32_bf16 v[2:5], v[14:17], v[18:21], v[2:5]
	s_waitcnt lgkmcnt(0)
	v_mfma_f32_16x16x32_bf16 v[2:5], v[10:13], v[22:25], v[2:5]
	ds_read_b128 v[10:13], v131 offset:128
	ds_read_b128 v[14:17], v131 offset:192
	s_waitcnt lgkmcnt(1)
	v_mfma_f32_16x16x32_bf16 v[6:9], v[10:13], v[18:21], v[6:9]
	s_nop 3
	v_add_f32_e64 v2, v26, -v2
	v_add_f32_e64 v3, v27, -v3
	v_lshlrev_b32_e32 v27, 16, v146
	v_lshlrev_b32_e32 v26, 16, v105
	v_pk_add_f32 v[4:5], v[26:27], v[4:5] neg_lo:[0,1] neg_hi:[0,1]
	v_cvt_pk_bf16_f32 v2, v2, v3
	v_cvt_pk_bf16_f32 v3, v4, v5
	ds_write_b64 v132, v[2:3]
	s_waitcnt lgkmcnt(0)
	s_barrier
	ds_read_b128 v[2:5], v133
	ds_read_b128 v[10:13], v134
	ds_read_b128 v[18:21], v133 offset:64
	v_mfma_f32_16x16x32_bf16 v[6:9], v[14:17], v[22:25], v[6:9]
	ds_read_b128 v[14:17], v134 offset:64
	v_mov_b32_e32 v105, v1
	s_waitcnt lgkmcnt(2)
	v_mfma_f32_16x16x32_bf16 v[2:5], v[2:5], v[10:13], v[6:9]
	s_nop 3
	v_lshl_add_u64 v[6:7], s[6:7], 0, v[0:1]
	v_lshl_add_u64 v[6:7], v[6:7], 0, v[104:105]
	s_waitcnt lgkmcnt(0)
	v_mfma_f32_16x16x32_bf16 v[2:5], v[18:21], v[14:17], v[2:5]
	s_mov_b64 s[6:7], 0xfc000
	v_lshl_add_u64 v[108:109], v[6:7], 0, s[6:7]
	v_lshl_add_u64 v[6:7], v[66:67], 1, v[108:109]
	s_waitcnt vmcnt(4)
	v_pk_mul_f32 v[20:21], v[106:107], v[32:33] op_sel_hi:[0,1]
	v_pk_mul_f32 v[18:19], v[106:107], v[30:31] op_sel_hi:[0,1]
	s_nop 1
	v_cvt_pk_bf16_f32 v2, v2, s0
	global_store_short v[6:7], v2, off
	ds_read_b128 v[6:9], v135 offset:34816
	v_cvt_pk_bf16_f32 v10, v3, s0
	v_lshl_add_u64 v[2:3], v[70:71], 1, v[108:109]
	global_store_short v[2:3], v10, off
	ds_read_b128 v[10:13], v135 offset:34880
	ds_read_b128 v[14:17], v136
	ds_read_b128 v[22:25], v136 offset:64
	s_waitcnt lgkmcnt(1)
	v_mfma_f32_16x16x32_bf16 v[14:17], v[6:9], v[14:17], v[18:21]
	s_nop 2
	ds_read_b128 v[18:21], v136 offset:2304
	ds_read_b128 v[26:29], v136 offset:2368
	v_cvt_pk_bf16_f32 v4, v4, s0
	s_waitcnt lgkmcnt(2)
	v_mfma_f32_16x16x32_bf16 v[14:17], v[10:13], v[22:25], v[14:17]
	v_mul_f32_e64 v24, v106, v36
	v_mul_f32_e64 v25, v106, v37
	v_pk_mul_f32 v[22:23], v[106:107], v[34:35] op_sel_hi:[0,1]
	v_lshl_add_u64 v[2:3], v[72:73], 1, v[108:109]
	global_store_short v[2:3], v4, off
	s_waitcnt lgkmcnt(1)
	v_mfma_f32_16x16x32_bf16 v[6:9], v[6:9], v[18:21], v[22:25]
	v_cvt_pk_bf16_f32 v4, v5, s0
	v_lshl_add_u64 v[2:3], v[74:75], 1, v[108:109]
	global_store_short v[2:3], v4, off
	s_waitcnt lgkmcnt(0)
	v_mfma_f32_16x16x32_bf16 v[2:5], v[10:13], v[26:29], v[6:9]
	s_nop 2
	v_cvt_pk_bf16_f32 v6, v14, v15
	v_cvt_pk_bf16_f32 v7, v16, v17
	s_nop 2
	v_cvt_pk_bf16_f32 v2, v2, v3
	v_cvt_pk_bf16_f32 v3, v4, v5
	ds_write_b64 v137, v[6:7]
	ds_write_b64 v137, v[2:3] offset:4352
	s_cbranch_scc0 .LBB0_282
